# attn v1 + branch-free 4-way interleaved RG-LRU gate math in the scan units
# speedup vs baseline: 1.0041x; 1.0041x over previous
; #define LAS __attribute__((address_space(3)))
; __device__ __forceinline__ unsigned cvt_pk(float lo, float hi) { unsigned r; asm("v_cvt_pk_bf16_f32 %0, %1, %2" : "=v"(r) : "v"(lo), "v"(hi)); return r; }
; __device__ __forceinline__ float bflo(unsigned w) { return __uint_as_float(w << 16); }
; __device__ __forceinline__ float bfhi(unsigned w) { return __uint_as_float(w & 0xffff0000u); }
; #define MFMA16(a, b, c) __builtin_amdgcn_mfma_f32_16x16x32_bf16((a), (b), (c), 0, 0, 0)
; template <int DIR>
; __device__ __forceinline__ void rnn_scan_unit(const Params& p, LAS unsigned char* lds, int b, int g) {
;     ...
;         { const int tl0 = lane >> 3, c8 = lane & 7;
; #pragma unroll
;           for (int hh = 0; hh < 2; ++hh) { const int tl = tl0 + 8 * hh;
;               f32x4 o0 = cbv[0], o1 = cbv[1];
; #pragma unroll
;               for (int j = 0; j < 4; ++j) { const u32x4 xw_ = *(const LAS u32x4*)(xrb + (tl + j) * 64 + 8 * c8);
;                   o0[0] += cwv[j][0][0] * bflo(xw_.x); o0[1] += cwv[j][0][1] * bfhi(xw_.x); o0[2] += cwv[j][0][2] * bflo(xw_.y); o0[3] += cwv[j][0][3] * bfhi(xw_.y);
;                   o1[0] += cwv[j][1][0] * bflo(xw_.z); o1[1] += cwv[j][1][1] * bfhi(xw_.z); o1[2] += cwv[j][1][2] * bflo(xw_.w); o1[3] += cwv[j][1][3] * bfhi(xw_.w); }
;               *(LAS f32x4*)(xcf + tl * XS + 8 * c8) = o0; *(LAS f32x4*)(xcf + tl * XS + 8 * c8 + 4) = o1; } }
;         asm volatile("s_waitcnt lgkmcnt(0)" ::: "memory");
;         { const int tt = fr; const bool valid = (t0 + tt) < TT;
;           bf16x8 af[2];
; #pragma unroll
;           for (int ks = 0; ks < 2; ++ks) { const f32x4 x0 = *(const LAS f32x4*)(xcf + tt * XS + 32 * ks + 8 * fq), x1 = *(const LAS f32x4*)(xcf + tt * XS + 32 * ks + 8 * fq + 4);
;               u32x4 w; w.x = cvt_pk(x0[0], x0[1]); w.y = cvt_pk(x0[2], x0[3]); w.z = cvt_pk(x1[0], x1[1]); w.w = cvt_pk(x1[2], x1[3]); af[ks] = __builtin_bit_cast(bf16x8, w); }
; #pragma unroll
;           for (int n = 0; n < 4; ++n) { const int c4 = 16 * n + 4 * fq;
;               f32x4 ra = *(const LAS f32x4*)(cst + c4), ia = *(const LAS f32x4*)(cst + 64 + c4);
; #pragma unroll
;               for (int ks = 0; ks < 2; ++ks) { ra = MFMA16(wreg[(0 * 4 + n) * 2 + ks], af[ks], ra); ia = MFMA16(wl[((1 * 4 + n) * 2 + ks) * 64 + lane], af[ks], ia); }
.LBB0_550:
	v_add_u32_e32 v0, v123, v125
	ds_read_b128 v[88:91], v0
	ds_read_b128 v[92:95], v0 offset:128
	ds_read_b128 v[96:99], v0 offset:256
	ds_read_b128 v[100:103], v0 offset:384
	v_mov_b32_e32 v113, 0
	s_waitcnt lgkmcnt(3)
	v_lshlrev_b32_e32 v104, 16, v88
	v_and_b32_e32 v105, 0xffff0000, v88
	v_lshlrev_b32_e32 v88, 16, v89
	v_and_b32_e32 v89, 0xffff0000, v89
	v_pk_fma_f32 v[104:105], v[36:37], v[104:105], v[40:41]
	s_waitcnt lgkmcnt(2)
	v_lshlrev_b32_e32 v106, 16, v92
	v_and_b32_e32 v107, 0xffff0000, v92
	v_pk_fma_f32 v[88:89], v[38:39], v[88:89], v[42:43]
	v_lshlrev_b32_e32 v92, 16, v93
	v_and_b32_e32 v93, 0xffff0000, v93
	v_pk_fma_f32 v[104:105], v[8:9], v[106:107], v[104:105]
	s_waitcnt lgkmcnt(1)
	v_lshlrev_b32_e32 v106, 16, v96
	v_and_b32_e32 v107, 0xffff0000, v96
	v_pk_fma_f32 v[88:89], v[10:11], v[92:93], v[88:89]
	v_lshlrev_b32_e32 v92, 16, v97
	v_and_b32_e32 v93, 0xffff0000, v97
	v_pk_fma_f32 v[104:105], v[12:13], v[106:107], v[104:105]
	s_waitcnt lgkmcnt(0)
	v_lshlrev_b32_e32 v106, 16, v100
	v_and_b32_e32 v107, 0xffff0000, v100
	v_pk_fma_f32 v[88:89], v[14:15], v[92:93], v[88:89]
	v_lshlrev_b32_e32 v92, 16, v101
	v_and_b32_e32 v93, 0xffff0000, v101
	v_pk_fma_f32 v[104:105], v[20:21], v[106:107], v[104:105]
	v_pk_fma_f32 v[106:107], v[22:23], v[92:93], v[88:89]
	v_lshlrev_b32_e32 v88, 16, v90
	v_and_b32_e32 v89, 0xffff0000, v90
	v_pk_fma_f32 v[88:89], v[28:29], v[88:89], v[32:33]
	v_lshlrev_b32_e32 v92, 16, v94
	v_and_b32_e32 v93, 0xffff0000, v94
	v_pk_fma_f32 v[88:89], v[4:5], v[92:93], v[88:89]
	v_lshlrev_b32_e32 v92, 16, v98
	v_and_b32_e32 v93, 0xffff0000, v98
	v_pk_fma_f32 v[88:89], v[16:17], v[92:93], v[88:89]
	v_lshlrev_b32_e32 v92, 16, v102
	v_and_b32_e32 v93, 0xffff0000, v102
	v_lshlrev_b32_e32 v90, 16, v91
	v_and_b32_e32 v91, 0xffff0000, v91
	v_pk_fma_f32 v[88:89], v[24:25], v[92:93], v[88:89]
	v_pk_fma_f32 v[90:91], v[30:31], v[90:91], v[34:35]
	v_lshlrev_b32_e32 v92, 16, v95
	v_and_b32_e32 v93, 0xffff0000, v95
	v_pk_fma_f32 v[90:91], v[6:7], v[92:93], v[90:91]
	v_lshlrev_b32_e32 v92, 16, v99
	v_and_b32_e32 v93, 0xffff0000, v99
	v_pk_fma_f32 v[90:91], v[18:19], v[92:93], v[90:91]
	v_lshlrev_b32_e32 v92, 16, v103
	v_and_b32_e32 v93, 0xffff0000, v103
	v_pk_fma_f32 v[90:91], v[26:27], v[92:93], v[90:91]
	ds_write_b128 v166, v[104:107] offset:2432
	ds_write_b128 v166, v[88:91] offset:2448
	ds_read_b128 v[88:91], v167
	ds_read_b128 v[92:95], v0 offset:1152
	ds_read_b128 v[96:99], v0 offset:1280
	ds_read_b128 v[100:103], v0 offset:1408
	v_add_u32_e32 v0, s19, v160
	s_waitcnt lgkmcnt(3)
	v_lshlrev_b32_e32 v104, 16, v88
	v_and_b32_e32 v105, 0xffff0000, v88
	v_lshlrev_b32_e32 v88, 16, v89
	v_and_b32_e32 v89, 0xffff0000, v89
	v_pk_fma_f32 v[104:105], v[36:37], v[104:105], v[40:41]
	s_waitcnt lgkmcnt(2)
	v_lshlrev_b32_e32 v106, 16, v92
	v_and_b32_e32 v107, 0xffff0000, v92
	v_pk_fma_f32 v[88:89], v[38:39], v[88:89], v[42:43]
	v_lshlrev_b32_e32 v92, 16, v93
	v_and_b32_e32 v93, 0xffff0000, v93
	v_pk_fma_f32 v[104:105], v[8:9], v[106:107], v[104:105]
	s_waitcnt lgkmcnt(1)
	v_lshlrev_b32_e32 v106, 16, v96
	v_and_b32_e32 v107, 0xffff0000, v96
	v_pk_fma_f32 v[88:89], v[10:11], v[92:93], v[88:89]
	v_lshlrev_b32_e32 v92, 16, v97
	v_and_b32_e32 v93, 0xffff0000, v97
	v_pk_fma_f32 v[104:105], v[12:13], v[106:107], v[104:105]
	s_waitcnt lgkmcnt(0)
	v_lshlrev_b32_e32 v106, 16, v100
	v_and_b32_e32 v107, 0xffff0000, v100
	v_pk_fma_f32 v[88:89], v[14:15], v[92:93], v[88:89]
	v_lshlrev_b32_e32 v92, 16, v101
	v_and_b32_e32 v93, 0xffff0000, v101
	v_pk_fma_f32 v[104:105], v[20:21], v[106:107], v[104:105]
	v_pk_fma_f32 v[106:107], v[22:23], v[92:93], v[88:89]
	v_lshlrev_b32_e32 v88, 16, v90
	v_and_b32_e32 v89, 0xffff0000, v90
	v_pk_fma_f32 v[88:89], v[28:29], v[88:89], v[32:33]
	v_lshlrev_b32_e32 v92, 16, v94
	v_and_b32_e32 v93, 0xffff0000, v94
	v_pk_fma_f32 v[88:89], v[4:5], v[92:93], v[88:89]
	v_lshlrev_b32_e32 v92, 16, v98
	v_and_b32_e32 v93, 0xffff0000, v98
	v_pk_fma_f32 v[88:89], v[16:17], v[92:93], v[88:89]
	v_lshlrev_b32_e32 v92, 16, v102
	v_and_b32_e32 v93, 0xffff0000, v102
	v_lshlrev_b32_e32 v90, 16, v91
	v_and_b32_e32 v91, 0xffff0000, v91
	v_pk_fma_f32 v[88:89], v[24:25], v[92:93], v[88:89]
	v_pk_fma_f32 v[90:91], v[30:31], v[90:91], v[34:35]
	v_lshlrev_b32_e32 v92, 16, v95
	v_and_b32_e32 v93, 0xffff0000, v95
	v_pk_fma_f32 v[90:91], v[6:7], v[92:93], v[90:91]
	v_lshlrev_b32_e32 v92, 16, v99
	v_and_b32_e32 v93, 0xffff0000, v99
	v_pk_fma_f32 v[90:91], v[18:19], v[92:93], v[90:91]
	v_lshlrev_b32_e32 v92, 16, v103
	v_and_b32_e32 v93, 0xffff0000, v103
	v_pk_fma_f32 v[90:91], v[26:27], v[92:93], v[90:91]
	ds_write_b128 v166, v[104:107] offset:4608
	ds_write_b128 v166, v[88:91] offset:4624
	s_waitcnt lgkmcnt(0)
	ds_read_b128 v[88:91], v168 offset:2432
	ds_read_b128 v[92:95], v168 offset:2448
	s_waitcnt lgkmcnt(1)
	v_cvt_pk_bf16_f32 v88, v88, v89
	v_cvt_pk_bf16_f32 v89, v90, v91
	s_waitcnt lgkmcnt(0)
	v_cvt_pk_bf16_f32 v90, v92, v93
	v_cvt_pk_bf16_f32 v91, v94, v95
	ds_read_b128 v[92:95], v168 offset:2560
	ds_read_b128 v[96:99], v168 offset:2576
	s_waitcnt lgkmcnt(1)
	v_cvt_pk_bf16_f32 v92, v92, v93
	v_cvt_pk_bf16_f32 v93, v94, v95
	s_waitcnt lgkmcnt(0)
	v_cvt_pk_bf16_f32 v94, v96, v97
	v_cvt_pk_bf16_f32 v95, v98, v99
	ds_read_b128 v[96:99], v126
	ds_read_b128 v[100:103], v127
	ds_read_b128 v[104:107], v117 offset:8192
	s_waitcnt lgkmcnt(2)
	v_mfma_f32_16x16x32_bf16 v[96:99], v[44:47], v[88:91], v[96:99]
	v_cmp_gt_i32_e64 s[16:17], s86, v0
	v_mov_b32_e32 v112, 0
	s_waitcnt lgkmcnt(0)
	v_mfma_f32_16x16x32_bf16 v[100:103], v[104:107], v[88:91], v[100:103]
	v_mfma_f32_16x16x32_bf16 v[104:107], v[48:51], v[92:95], v[96:99]
	s_nop 2
	ds_read_b128 v[96:99], v117 offset:9216
	s_waitcnt lgkmcnt(0)
; #define LAS __attribute__((address_space(3)))
; #define MFMA16(a, b, c) __builtin_amdgcn_mfma_f32_16x16x32_bf16((a), (b), (c), 0, 0, 0)
; template <int DIR>
; __device__ __forceinline__ void rnn_scan_unit(const Params& p, LAS unsigned char* lds, int b, int g) {
;     ...
;           for (int n = 0; n < 4; ++n) { const int c4 = 16 * n + 4 * fq;
;               f32x4 ra = *(const LAS f32x4*)(cst + c4), ia = *(const LAS f32x4*)(cst + 64 + c4);
; #pragma unroll
;               for (int ks = 0; ks < 2; ++ks) { ra = MFMA16(wreg[(0 * 4 + n) * 2 + ks], af[ks], ra); ia = MFMA16(wl[((1 * 4 + n) * 2 + ks) * 64 + lane], af[ks], ia); }
;               const f32x4 xv = *(const LAS f32x4*)(xcf + tt * XS + c4);
;               const f32x4 spv = *(const LAS f32x4*)(cst + 128 + c4);
;               f32x4 av, bv;
; #pragma unroll
;               for (int i = 0; i < 4; ++i) { const float r = __builtin_amdgcn_rcpf(1.0f + __builtin_amdgcn_exp2f(ra[i])), ig = __builtin_amdgcn_rcpf(1.0f + __builtin_amdgcn_exp2f(ia[i]));
;                   const float a = __builtin_amdgcn_exp2f(r * spv[i]); const float em = fmaf(-a, a, 1.0f);
;                   av[i] = valid ? a : 1.0f; bv[i] = valid ? __builtin_amdgcn_sqrtf(fmaxf(em, 0.0f)) * ig * xv[i] : 0.0f; }
;               *(LAS f32x4*)(al + tt * 64 + c4) = av; *(LAS f32x4*)(bl + tt * 64 + c4) = bv; } }
	v_mfma_f32_16x16x32_bf16 v[100:103], v[96:99], v[92:95], v[100:103]
	s_nop 1
	ds_read_b128 v[96:99], v128 offset:2432
	ds_read_b128 v[108:111], v129
	v_exp_f32_e32 v104, v104
	v_exp_f32_e32 v105, v105
	v_exp_f32_e32 v106, v106
	v_exp_f32_e32 v107, v107
	v_exp_f32_e32 v100, v100
	v_exp_f32_e32 v101, v101
	v_exp_f32_e32 v102, v102
	v_exp_f32_e32 v103, v103
	v_add_f32_e32 v104, 1.0, v104
	v_add_f32_e32 v105, 1.0, v105
	v_add_f32_e32 v106, 1.0, v106
	v_add_f32_e32 v107, 1.0, v107
	v_add_f32_e32 v100, 1.0, v100
	v_add_f32_e32 v101, 1.0, v101
	v_add_f32_e32 v102, 1.0, v102
	v_add_f32_e32 v103, 1.0, v103
	v_rcp_f32_e32 v104, v104
	v_rcp_f32_e32 v105, v105
	v_rcp_f32_e32 v106, v106
	v_rcp_f32_e32 v107, v107
	v_rcp_f32_e32 v100, v100
	v_rcp_f32_e32 v101, v101
	v_rcp_f32_e32 v102, v102
	v_rcp_f32_e32 v103, v103
	s_waitcnt lgkmcnt(0)
	v_mul_f32_e32 v104, v104, v108
	v_mul_f32_e32 v105, v105, v109
	v_mul_f32_e32 v106, v106, v110
	v_mul_f32_e32 v107, v107, v111
	v_exp_f32_e32 v104, v104
	v_exp_f32_e32 v105, v105
	v_exp_f32_e32 v106, v106
	v_exp_f32_e32 v107, v107
	v_fma_f32 v112, -v104, v104, 1.0
	v_fma_f32 v113, -v105, v105, 1.0
	v_fma_f32 v114, -v106, v106, 1.0
	v_fma_f32 v115, -v107, v107, 1.0
	v_max_f32_e32 v112, 0, v112
	v_max_f32_e32 v113, 0, v113
	v_max_f32_e32 v114, 0, v114
	v_max_f32_e32 v115, 0, v115
	v_sqrt_f32_e32 v112, v112
	v_sqrt_f32_e32 v113, v113
	v_sqrt_f32_e32 v114, v114
	v_sqrt_f32_e32 v115, v115
	v_mul_f32_e32 v100, v100, v112
	v_mul_f32_e32 v101, v101, v113
	v_mul_f32_e32 v102, v102, v114
	v_mul_f32_e32 v103, v103, v115
	v_mul_f32_e32 v112, v96, v100
	v_mul_f32_e32 v113, v97, v101
	v_mul_f32_e32 v114, v98, v102
	v_mul_f32_e32 v115, v99, v103
	v_cndmask_b32_e64 v112, 0, v112, s[16:17]
	v_cndmask_b32_e64 v113, 0, v113, s[16:17]
	v_cndmask_b32_e64 v114, 0, v114, s[16:17]
	v_cndmask_b32_e64 v115, 0, v115, s[16:17]
	v_cndmask_b32_e64 v98, 1.0, v104, s[16:17]
	v_cndmask_b32_e64 v99, 1.0, v105, s[16:17]
	v_cndmask_b32_e64 v100, 1.0, v106, s[16:17]
	v_cndmask_b32_e64 v101, 1.0, v107, s[16:17]
	ds_write_b128 v130, v[98:101] offset:6784
	ds_write_b128 v130, v[112:115] offset:10880
	ds_read_b128 v[96:99], v131
	ds_read_b128 v[100:103], v132
	ds_read_b128 v[104:107], v117 offset:10240
	s_waitcnt lgkmcnt(2)
	v_mfma_f32_16x16x32_bf16 v[96:99], v[52:55], v[88:91], v[96:99]
	v_mov_b32_e32 v113, 0
	v_mov_b32_e32 v112, 0
	s_waitcnt lgkmcnt(0)
	v_mfma_f32_16x16x32_bf16 v[100:103], v[104:107], v[88:91], v[100:103]
	v_mfma_f32_16x16x32_bf16 v[104:107], v[56:59], v[92:95], v[96:99]
	s_nop 2
	ds_read_b128 v[96:99], v117 offset:11264
	s_waitcnt lgkmcnt(0)
	v_mfma_f32_16x16x32_bf16 v[96:99], v[96:99], v[92:95], v[100:103]
	s_nop 1
	ds_read_b128 v[100:103], v128 offset:2496
	ds_read_b128 v[108:111], v133
	v_exp_f32_e32 v104, v104
	v_exp_f32_e32 v105, v105
	v_exp_f32_e32 v106, v106
	v_exp_f32_e32 v107, v107
	v_exp_f32_e32 v96, v96
	v_exp_f32_e32 v97, v97
	v_exp_f32_e32 v98, v98
	v_exp_f32_e32 v99, v99
	v_add_f32_e32 v104, 1.0, v104
	v_add_f32_e32 v105, 1.0, v105
	v_add_f32_e32 v106, 1.0, v106
	v_add_f32_e32 v107, 1.0, v107
	v_add_f32_e32 v96, 1.0, v96
	v_add_f32_e32 v97, 1.0, v97
	v_add_f32_e32 v98, 1.0, v98
	v_add_f32_e32 v99, 1.0, v99
	v_rcp_f32_e32 v104, v104
	v_rcp_f32_e32 v105, v105
	v_rcp_f32_e32 v106, v106
	v_rcp_f32_e32 v107, v107
	v_rcp_f32_e32 v96, v96
	v_rcp_f32_e32 v97, v97
	v_rcp_f32_e32 v98, v98
	v_rcp_f32_e32 v99, v99
	s_waitcnt lgkmcnt(0)
	v_mul_f32_e32 v104, v104, v108
	v_mul_f32_e32 v105, v105, v109
	v_mul_f32_e32 v106, v106, v110
	v_mul_f32_e32 v107, v107, v111
	v_exp_f32_e32 v104, v104
	v_exp_f32_e32 v105, v105
	v_exp_f32_e32 v106, v106
	v_exp_f32_e32 v107, v107
	v_fma_f32 v112, -v104, v104, 1.0
	v_fma_f32 v113, -v105, v105, 1.0
	v_fma_f32 v114, -v106, v106, 1.0
	v_fma_f32 v115, -v107, v107, 1.0
	v_max_f32_e32 v112, 0, v112
	v_max_f32_e32 v113, 0, v113
	v_max_f32_e32 v114, 0, v114
	v_max_f32_e32 v115, 0, v115
	v_sqrt_f32_e32 v112, v112
	v_sqrt_f32_e32 v113, v113
	v_sqrt_f32_e32 v114, v114
	v_sqrt_f32_e32 v115, v115
	v_mul_f32_e32 v96, v96, v112
	v_mul_f32_e32 v97, v97, v113
	v_mul_f32_e32 v98, v98, v114
	v_mul_f32_e32 v99, v99, v115
	v_mul_f32_e32 v112, v100, v96
	v_mul_f32_e32 v113, v101, v97
	v_mul_f32_e32 v114, v102, v98
	v_mul_f32_e32 v115, v103, v99
	v_cndmask_b32_e64 v112, 0, v112, s[16:17]
	v_cndmask_b32_e64 v113, 0, v113, s[16:17]
	v_cndmask_b32_e64 v114, 0, v114, s[16:17]
	v_cndmask_b32_e64 v115, 0, v115, s[16:17]
	v_cndmask_b32_e64 v98, 1.0, v104, s[16:17]
	v_cndmask_b32_e64 v99, 1.0, v105, s[16:17]
	v_cndmask_b32_e64 v100, 1.0, v106, s[16:17]
	v_cndmask_b32_e64 v101, 1.0, v107, s[16:17]
	ds_write_b128 v130, v[98:101] offset:6848
	ds_write_b128 v130, v[112:115] offset:10944
	ds_read_b128 v[96:99], v134
	ds_read_b128 v[100:103], v135
	ds_read_b128 v[104:107], v117 offset:12288
	s_waitcnt lgkmcnt(2)
	v_mfma_f32_16x16x32_bf16 v[96:99], v[60:63], v[88:91], v[96:99]
	v_mov_b32_e32 v113, 0
	v_mov_b32_e32 v112, 0
	s_waitcnt lgkmcnt(0)
	v_mfma_f32_16x16x32_bf16 v[100:103], v[104:107], v[88:91], v[100:103]
	v_mfma_f32_16x16x32_bf16 v[104:107], v[64:67], v[92:95], v[96:99]
	s_nop 2
	ds_read_b128 v[96:99], v117 offset:13312
	s_waitcnt lgkmcnt(0)
	v_mfma_f32_16x16x32_bf16 v[96:99], v[96:99], v[92:95], v[100:103]
	s_nop 1
	ds_read_b128 v[100:103], v128 offset:2560
	ds_read_b128 v[108:111], v136
	v_exp_f32_e32 v104, v104
	v_exp_f32_e32 v105, v105
	v_exp_f32_e32 v106, v106
	v_exp_f32_e32 v107, v107
	v_exp_f32_e32 v96, v96
	v_exp_f32_e32 v97, v97
	v_exp_f32_e32 v98, v98
	v_exp_f32_e32 v99, v99
	v_add_f32_e32 v104, 1.0, v104
	v_add_f32_e32 v105, 1.0, v105
	v_add_f32_e32 v106, 1.0, v106
	v_add_f32_e32 v107, 1.0, v107
	v_add_f32_e32 v96, 1.0, v96
	v_add_f32_e32 v97, 1.0, v97
	v_add_f32_e32 v98, 1.0, v98
	v_add_f32_e32 v99, 1.0, v99
	v_rcp_f32_e32 v104, v104
	v_rcp_f32_e32 v105, v105
	v_rcp_f32_e32 v106, v106
	v_rcp_f32_e32 v107, v107
	v_rcp_f32_e32 v96, v96
	v_rcp_f32_e32 v97, v97
	v_rcp_f32_e32 v98, v98
	v_rcp_f32_e32 v99, v99
	s_waitcnt lgkmcnt(0)
; #define LAS __attribute__((address_space(3)))
; #define MFMA16(a, b, c) __builtin_amdgcn_mfma_f32_16x16x32_bf16((a), (b), (c), 0, 0, 0)
; #define LDS_BARRIER() asm volatile("s_waitcnt lgkmcnt(0)\n\ts_barrier" ::: "memory")
; template <int DIR>
; __device__ __forceinline__ void rnn_scan_unit(const Params& p, LAS unsigned char* lds, int b, int g) {
;     ...
;           for (int n = 0; n < 4; ++n) { const int c4 = 16 * n + 4 * fq;
;               f32x4 ra = *(const LAS f32x4*)(cst + c4), ia = *(const LAS f32x4*)(cst + 64 + c4);
; #pragma unroll
;               for (int ks = 0; ks < 2; ++ks) { ra = MFMA16(wreg[(0 * 4 + n) * 2 + ks], af[ks], ra); ia = MFMA16(wl[((1 * 4 + n) * 2 + ks) * 64 + lane], af[ks], ia); }
;               const f32x4 xv = *(const LAS f32x4*)(xcf + tt * XS + c4);
;               const f32x4 spv = *(const LAS f32x4*)(cst + 128 + c4);
;               f32x4 av, bv;
; #pragma unroll
;               for (int i = 0; i < 4; ++i) { const float r = __builtin_amdgcn_rcpf(1.0f + __builtin_amdgcn_exp2f(ra[i])), ig = __builtin_amdgcn_rcpf(1.0f + __builtin_amdgcn_exp2f(ia[i]));
;                   const float a = __builtin_amdgcn_exp2f(r * spv[i]); const float em = fmaf(-a, a, 1.0f);
;                   av[i] = valid ? a : 1.0f; bv[i] = valid ? __builtin_amdgcn_sqrtf(fmaxf(em, 0.0f)) * ig * xv[i] : 0.0f; }
;               *(LAS f32x4*)(al + tt * 64 + c4) = av; *(LAS f32x4*)(bl + tt * 64 + c4) = bv; } }
;         asm volatile("s_waitcnt lgkmcnt(0)" ::: "memory");
;         LAS float* sgA = sg + (ci & 1) * 1024; LAS float* sgB = sgA + 512;
;         float av_[16], bv_[16];
;         { float A = 1.f, B = 0.f;
; #pragma unroll
;           for (int k = 0; k < 16; ++k) { const int tt = DIR == 0 ? k : 15 - k; av_[k] = al[tt * 64 + ch]; bv_[k] = bl[tt * 64 + ch]; B = av_[k] * B + bv_[k]; A *= av_[k]; }
;           sgA[seg * 64 + ch] = A; sgB[seg * 64 + ch] = B; }
;         LDS_BARRIER();
	v_mul_f32_e32 v104, v104, v108
	v_mul_f32_e32 v105, v105, v109
	v_mul_f32_e32 v106, v106, v110
	v_mul_f32_e32 v107, v107, v111
	v_exp_f32_e32 v104, v104
	v_exp_f32_e32 v105, v105
	v_exp_f32_e32 v106, v106
	v_exp_f32_e32 v107, v107
	v_fma_f32 v112, -v104, v104, 1.0
	v_fma_f32 v113, -v105, v105, 1.0
	v_fma_f32 v114, -v106, v106, 1.0
	v_fma_f32 v115, -v107, v107, 1.0
	v_max_f32_e32 v112, 0, v112
	v_max_f32_e32 v113, 0, v113
	v_max_f32_e32 v114, 0, v114
	v_max_f32_e32 v115, 0, v115
	v_sqrt_f32_e32 v112, v112
	v_sqrt_f32_e32 v113, v113
	v_sqrt_f32_e32 v114, v114
	v_sqrt_f32_e32 v115, v115
	v_mul_f32_e32 v96, v96, v112
	v_mul_f32_e32 v97, v97, v113
	v_mul_f32_e32 v98, v98, v114
	v_mul_f32_e32 v99, v99, v115
	v_mul_f32_e32 v112, v100, v96
	v_mul_f32_e32 v113, v101, v97
	v_mul_f32_e32 v114, v102, v98
	v_mul_f32_e32 v115, v103, v99
	v_cndmask_b32_e64 v112, 0, v112, s[16:17]
	v_cndmask_b32_e64 v113, 0, v113, s[16:17]
	v_cndmask_b32_e64 v114, 0, v114, s[16:17]
	v_cndmask_b32_e64 v115, 0, v115, s[16:17]
	v_cndmask_b32_e64 v98, 1.0, v104, s[16:17]
	v_cndmask_b32_e64 v99, 1.0, v105, s[16:17]
	v_cndmask_b32_e64 v100, 1.0, v106, s[16:17]
	v_cndmask_b32_e64 v101, 1.0, v107, s[16:17]
	ds_write_b128 v130, v[98:101] offset:6912
	ds_write_b128 v130, v[112:115] offset:11008
	ds_read_b128 v[96:99], v137
	ds_read_b128 v[100:103], v138
	ds_read_b128 v[104:107], v117 offset:14336
	s_waitcnt lgkmcnt(2)
	v_mfma_f32_16x16x32_bf16 v[96:99], v[68:71], v[88:91], v[96:99]
	s_waitcnt lgkmcnt(0)
	v_mfma_f32_16x16x32_bf16 v[88:91], v[104:107], v[88:91], v[100:103]
	v_mov_b32_e32 v105, 0
	s_nop 1
	ds_read_b128 v[100:103], v117 offset:15360
	v_mov_b32_e32 v104, 0
	v_mfma_f32_16x16x32_bf16 v[96:99], v[72:75], v[92:95], v[96:99]
	s_waitcnt lgkmcnt(0)
	v_mfma_f32_16x16x32_bf16 v[88:91], v[100:103], v[92:95], v[88:91]
	ds_read_b128 v[92:95], v128 offset:2624
	ds_read_b128 v[100:103], v139
	s_nop 3
	v_exp_f32_e32 v96, v96
	v_exp_f32_e32 v97, v97
	v_exp_f32_e32 v98, v98
	v_exp_f32_e32 v99, v99
	v_exp_f32_e32 v88, v88
	v_exp_f32_e32 v89, v89
	v_exp_f32_e32 v90, v90
	v_exp_f32_e32 v91, v91
	v_add_f32_e32 v96, 1.0, v96
	v_add_f32_e32 v97, 1.0, v97
	v_add_f32_e32 v98, 1.0, v98
	v_add_f32_e32 v99, 1.0, v99
	v_add_f32_e32 v88, 1.0, v88
	v_add_f32_e32 v89, 1.0, v89
	v_add_f32_e32 v90, 1.0, v90
	v_add_f32_e32 v91, 1.0, v91
	v_rcp_f32_e32 v96, v96
	v_rcp_f32_e32 v97, v97
	v_rcp_f32_e32 v98, v98
	v_rcp_f32_e32 v99, v99
	v_rcp_f32_e32 v88, v88
	v_rcp_f32_e32 v89, v89
	v_rcp_f32_e32 v90, v90
	v_rcp_f32_e32 v91, v91
	s_waitcnt lgkmcnt(0)
	v_mul_f32_e32 v96, v96, v100
	v_mul_f32_e32 v97, v97, v101
	v_mul_f32_e32 v98, v98, v102
	v_mul_f32_e32 v99, v99, v103
	v_exp_f32_e32 v96, v96
	v_exp_f32_e32 v97, v97
	v_exp_f32_e32 v98, v98
	v_exp_f32_e32 v99, v99
	v_fma_f32 v104, -v96, v96, 1.0
	v_fma_f32 v105, -v97, v97, 1.0
	v_fma_f32 v106, -v98, v98, 1.0
	v_fma_f32 v107, -v99, v99, 1.0
	v_max_f32_e32 v104, 0, v104
	v_max_f32_e32 v105, 0, v105
	v_max_f32_e32 v106, 0, v106
	v_max_f32_e32 v107, 0, v107
	v_sqrt_f32_e32 v104, v104
	v_sqrt_f32_e32 v105, v105
	v_sqrt_f32_e32 v106, v106
	v_sqrt_f32_e32 v107, v107
	v_mul_f32_e32 v88, v88, v104
	v_mul_f32_e32 v89, v89, v105
	v_mul_f32_e32 v90, v90, v106
	v_mul_f32_e32 v91, v91, v107
	v_mul_f32_e32 v104, v92, v88
	v_mul_f32_e32 v105, v93, v89
	v_mul_f32_e32 v106, v94, v90
	v_mul_f32_e32 v107, v95, v91
	v_cndmask_b32_e64 v104, 0, v104, s[16:17]
	v_cndmask_b32_e64 v105, 0, v105, s[16:17]
	v_cndmask_b32_e64 v106, 0, v106, s[16:17]
	v_cndmask_b32_e64 v107, 0, v107, s[16:17]
	v_cndmask_b32_e64 v90, 1.0, v96, s[16:17]
	v_cndmask_b32_e64 v91, 1.0, v97, s[16:17]
	v_cndmask_b32_e64 v92, 1.0, v98, s[16:17]
	v_cndmask_b32_e64 v93, 1.0, v99, s[16:17]
	ds_write_b128 v130, v[90:93] offset:6976
	ds_write_b128 v130, v[104:107] offset:11072
	s_waitcnt lgkmcnt(0)
	v_add_u32_e32 v169, 0x80, v154
	ds_read2st64_b32 v[88:89], v169 offset0:41 offset1:42
	ds_read2st64_b32 v[90:91], v169 offset0:55 offset1:57
	v_add_u32_e32 v3, 0x80, v155
	ds_read2st64_b32 v[92:93], v3 offset0:41 offset1:57
	ds_read2st64_b32 v[94:95], v169 offset0:38 offset1:39
	ds_read2st64_b32 v[172:173], v169 offset0:43 offset1:44
	ds_read2st64_b32 v[98:99], v169 offset0:36 offset1:37
	ds_read2st64_b32 v[102:103], v169 offset0:34 offset1:35
	ds_read2st64_b32 v[96:97], v169 offset0:53 offset1:54
	s_waitcnt lgkmcnt(6)
	v_fma_f32 v0, 0, v88, v91
	ds_read2st64_b32 v[100:101], v169 offset0:51 offset1:52
	ds_read2st64_b32 v[104:105], v169 offset0:49 offset1:50
	ds_read2st64_b32 v[108:109], v169 offset0:47 offset1:48
	ds_read2st64_b32 v[114:115], v169 offset0:45 offset1:46
	s_waitcnt lgkmcnt(9)
	v_fma_f32 v0, v0, v92, v93
	v_mul_f32_e32 v3, v88, v92
	s_waitcnt lgkmcnt(8)
	v_fma_f32 v0, v0, v95, v90
	v_mul_f32_e32 v3, v3, v95
	s_waitcnt lgkmcnt(4)
	v_fma_f32 v0, v0, v94, v97
	v_mul_f32_e32 v3, v3, v94
	ds_read2st64_b32 v[106:107], v169 offset0:32 offset1:33
	ds_read2st64_b32 v[112:113], v169 offset0:30 offset1:31
	ds_read2st64_b32 v[170:171], v169 offset0:28 offset1:29
	ds_read2st64_b32 v[174:175], v169 offset0:26 offset1:27
	v_fma_f32 v0, v0, v99, v96
	v_mul_f32_e32 v3, v3, v99
	s_waitcnt lgkmcnt(7)
	v_fma_f32 v0, v0, v98, v101
	v_mul_f32_e32 v3, v3, v98
	v_fma_f32 v0, v0, v103, v100
	v_mul_f32_e32 v3, v3, v103
	s_waitcnt lgkmcnt(6)
	v_fma_f32 v0, v0, v102, v105
	v_mul_f32_e32 v3, v3, v102
	s_waitcnt lgkmcnt(3)
	v_fma_f32 v0, v0, v107, v104
	v_mul_f32_e32 v3, v3, v107
	v_fma_f32 v0, v0, v106, v109
	v_mul_f32_e32 v3, v3, v106
	s_waitcnt lgkmcnt(2)
	v_fma_f32 v0, v0, v113, v108
	v_mul_f32_e32 v3, v3, v113
	s_and_b32 s16, s34, 0x400
	v_fma_f32 v0, v0, v112, v115
	v_mul_f32_e32 v3, v3, v112
	s_lshl_b32 s16, s16, 2
	s_waitcnt lgkmcnt(1)
	v_fma_f32 v0, v0, v171, v114
	v_mul_f32_e32 v3, v3, v171
	s_add_i32 s16, s16, 0
	v_fma_f32 v0, v0, v170, v173
	v_mul_f32_e32 v3, v3, v170
	s_add_i32 s16, s16, 0x1d400
	s_waitcnt lgkmcnt(0)
	v_fma_f32 v0, v0, v175, v172
	v_mul_f32_e32 v3, v3, v175
	v_fma_f32 v0, v0, v174, v89
	v_mul_f32_e32 v3, v3, v174
	v_lshl_add_u32 v110, v116, 2, s16
	ds_write2st64_b32 v110, v3, v0 offset1:8
	s_waitcnt lgkmcnt(0)
	s_barrier
; #define LAS __attribute__((address_space(3)))
; __device__ __forceinline__ unsigned cvt_pk(float lo, float hi) { unsigned r; asm("v_cvt_pk_bf16_f32 %0, %1, %2" : "=v"(r) : "v"(lo), "v"(hi)); return r; }
; template <int DIR>
; __device__ __forceinline__ void rnn_scan_unit(const Params& p, LAS unsigned char* lds, int b, int g) {
;     ...
;         float h = hcar, hin = hcar;
; #pragma unroll
;         for (int s = 0; s < 8; ++s) { const int sx = DIR == 0 ? s : 7 - s; hin = (sx == seg) ? h : hin; h = sgA[sx * 64 + ch] * h + sgB[sx * 64 + ch]; }
;         hcar = h;
; #pragma unroll
;         for (int k = 0; k < 16; ++k) { const int tt = DIR == 0 ? k : 15 - k; hin = av_[k] * hin + bv_[k]; bl[tt * 64 + ch] = hin; }
;         asm volatile("s_waitcnt lgkmcnt(0)" ::: "memory");
;         { const int tk = lane >> 2, cq4 = lane & 3;
;           if (t0 + tk < TT) { const LAS float* src = bl + tk * 64 + 16 * cq4;
;               const f32x4 x0 = *(const LAS f32x4*)(src), x1 = *(const LAS f32x4*)(src + 4), x2 = *(const LAS f32x4*)(src + 8), x3 = *(const LAS f32x4*)(src + 12);
;               u32x4 w0, w1; w0.x = cvt_pk(x0[0], x0[1]); w0.y = cvt_pk(x0[2], x0[3]); w0.z = cvt_pk(x1[0], x1[1]); w0.w = cvt_pk(x1[2], x1[3]);
;               w1.x = cvt_pk(x2[0], x2[1]); w1.y = cvt_pk(x2[2], x2[3]); w1.z = cvt_pk(x3[0], x3[1]); w1.w = cvt_pk(x3[2], x3[3]);
;               bf16_t* hp = H + ((size_t)b * TT + t0 + tk) * 512 + 64 * g + 16 * cq4;
;               *(u32x4*)hp = w0; *(u32x4*)(hp + 8) = w1; } }
;         asm volatile("s_waitcnt lgkmcnt(0)" ::: "memory");
	v_lshl_add_u32 v0, v122, 2, s16
	ds_read2st64_b32 v[110:111], v0 offset0:6 offset1:7
	ds_read2st64_b32 v[176:177], v0 offset0:14 offset1:15
	s_waitcnt lgkmcnt(0)
	v_fma_f32 v3, v2, v111, v177
	v_cndmask_b32_e64 v2, v2, v3, s[0:1]
	v_fmac_f32_e32 v176, v3, v110
	v_cndmask_b32_e64 v177, v2, v176, s[2:3]
	ds_read2st64_b32 v[2:3], v0 offset0:4 offset1:5
	ds_read2st64_b32 v[110:111], v0 offset0:12 offset1:13
	s_waitcnt lgkmcnt(0)
	v_fma_f32 v3, v176, v3, v111
	v_cndmask_b32_e64 v111, v177, v3, s[4:5]
	v_fmac_f32_e32 v110, v3, v2
	ds_read2st64_b32 v[2:3], v0 offset0:2 offset1:3
	ds_read2st64_b32 v[176:177], v0 offset0:10 offset1:11
	v_cndmask_b32_e64 v111, v111, v110, s[8:9]
	s_waitcnt lgkmcnt(0)
	v_fma_f32 v3, v110, v3, v177
	v_cndmask_b32_e64 v110, v111, v3, s[10:11]
	v_fmac_f32_e32 v176, v3, v2
	v_cndmask_b32_e64 v177, v110, v176, s[12:13]
	ds_read2st64_b32 v[110:111], v0 offset1:1
	ds_read2st64_b32 v[2:3], v0 offset0:8 offset1:9
	s_waitcnt lgkmcnt(0)
	v_fma_f32 v0, v176, v111, v3
	v_cndmask_b32_e64 v3, v177, v0, s[14:15]
	v_fma_f32 v3, v88, v3, v91
	v_fmac_f32_e32 v93, v92, v3
	v_fmac_f32_e32 v90, v95, v93
	ds_write_b32 v154, v3 offset:14720
	v_fma_f32 v3, v94, v90, v97
	v_fmac_f32_e32 v96, v99, v3
	ds_write2st64_b32 v169, v3, v90 offset0:54 offset1:55
	v_fma_f32 v3, v98, v96, v101
	v_fmac_f32_e32 v100, v103, v3
	ds_write2st64_b32 v169, v3, v96 offset0:52 offset1:53
	v_fma_f32 v3, v102, v100, v105
	v_fmac_f32_e32 v104, v107, v3
	ds_write2st64_b32 v169, v3, v100 offset0:50 offset1:51
	v_fma_f32 v3, v106, v104, v109
	v_fmac_f32_e32 v108, v113, v3
	ds_write2st64_b32 v169, v3, v104 offset0:48 offset1:49
	v_fma_f32 v3, v112, v108, v115
	v_fmac_f32_e32 v114, v171, v3
	ds_write2st64_b32 v169, v3, v108 offset0:46 offset1:47
	v_fma_f32 v3, v170, v114, v173
	v_fmac_f32_e32 v172, v175, v3
	v_fmac_f32_e32 v89, v174, v172
	ds_write_b32 v155, v93 offset:14720
	ds_write2st64_b32 v169, v3, v114 offset0:44 offset1:45
	ds_write2st64_b32 v169, v89, v172 offset0:42 offset1:43
	s_waitcnt lgkmcnt(0)
	v_add_u32_e32 v3, s19, v159
	v_cmp_gt_i32_e64 s[16:17], s86, v3
	s_and_saveexec_b64 s[76:77], s[16:17]
	s_cbranch_execz .LBB0_539
	ds_read_b128 v[88:91], v124 offset:10880
	ds_read_b128 v[92:95], v124 offset:10896
	ds_read_b128 v[96:99], v124 offset:10912
	ds_read_b128 v[100:103], v124 offset:10928
	s_waitcnt lgkmcnt(3)
	v_cvt_pk_bf16_f32 v88, v88, v89
	v_cvt_pk_bf16_f32 v89, v90, v91
	s_waitcnt lgkmcnt(2)
	v_cvt_pk_bf16_f32 v90, v92, v93
	v_cvt_pk_bf16_f32 v91, v94, v95
	s_waitcnt lgkmcnt(1)
	v_cvt_pk_bf16_f32 v92, v96, v97
	v_cvt_pk_bf16_f32 v93, v98, v99
	s_waitcnt lgkmcnt(0)
	v_cvt_pk_bf16_f32 v94, v100, v101
	v_cvt_pk_bf16_f32 v95, v102, v103
	global_store_dwordx4 v[120:121], v[88:91], off
	global_store_dwordx4 v[120:121], v[92:95], off offset:16
	s_branch .LBB0_539

; #define LAS __attribute__((address_space(3)))
; __device__ __forceinline__ unsigned cvt_pk(float lo, float hi) { unsigned r; asm("v_cvt_pk_bf16_f32 %0, %1, %2" : "=v"(r) : "v"(lo), "v"(hi)); return r; }
; __device__ __forceinline__ float bflo(unsigned w) { return __uint_as_float(w << 16); }
; __device__ __forceinline__ float bfhi(unsigned w) { return __uint_as_float(w & 0xffff0000u); }
; #define MFMA16(a, b, c) __builtin_amdgcn_mfma_f32_16x16x32_bf16((a), (b), (c), 0, 0, 0)
; template <int DIR>
; __device__ __forceinline__ void rnn_scan_unit(const Params& p, LAS unsigned char* lds, int b, int g) {
;     ...
;         { const int tl0 = lane >> 3, c8 = lane & 7;
; #pragma unroll
;           for (int hh = 0; hh < 2; ++hh) { const int tl = tl0 + 8 * hh;
;               f32x4 o0 = cbv[0], o1 = cbv[1];
; #pragma unroll
;               for (int j = 0; j < 4; ++j) { const u32x4 xw_ = *(const LAS u32x4*)(xrb + (tl + j) * 64 + 8 * c8);
;                   o0[0] += cwv[j][0][0] * bflo(xw_.x); o0[1] += cwv[j][0][1] * bfhi(xw_.x); o0[2] += cwv[j][0][2] * bflo(xw_.y); o0[3] += cwv[j][0][3] * bfhi(xw_.y);
;                   o1[0] += cwv[j][1][0] * bflo(xw_.z); o1[1] += cwv[j][1][1] * bfhi(xw_.z); o1[2] += cwv[j][1][2] * bflo(xw_.w); o1[3] += cwv[j][1][3] * bfhi(xw_.w); }
;               *(LAS f32x4*)(xcf + tl * XS + 8 * c8) = o0; *(LAS f32x4*)(xcf + tl * XS + 8 * c8 + 4) = o1; } }
;         asm volatile("s_waitcnt lgkmcnt(0)" ::: "memory");
;         { const int tt = fr; const bool valid = (t0 + tt) < TT;
;           bf16x8 af[2];
; #pragma unroll
;           for (int ks = 0; ks < 2; ++ks) { const f32x4 x0 = *(const LAS f32x4*)(xcf + tt * XS + 32 * ks + 8 * fq), x1 = *(const LAS f32x4*)(xcf + tt * XS + 32 * ks + 8 * fq + 4);
;               u32x4 w; w.x = cvt_pk(x0[0], x0[1]); w.y = cvt_pk(x0[2], x0[3]); w.z = cvt_pk(x1[0], x1[1]); w.w = cvt_pk(x1[2], x1[3]); af[ks] = __builtin_bit_cast(bf16x8, w); }
; #pragma unroll
;           for (int n = 0; n < 4; ++n) { const int c4 = 16 * n + 4 * fq;
;               f32x4 ra = *(const LAS f32x4*)(cst + c4), ia = *(const LAS f32x4*)(cst + 64 + c4);
; #pragma unroll
;               for (int ks = 0; ks < 2; ++ks) { ra = MFMA16(wreg[(0 * 4 + n) * 2 + ks], af[ks], ra); ia = MFMA16(wl[((1 * 4 + n) * 2 + ks) * 64 + lane], af[ks], ia); }
.LBB0_606:
	v_add_u32_e32 v0, v123, v126
	ds_read_b128 v[88:91], v0
	ds_read_b128 v[92:95], v0 offset:128
	ds_read_b128 v[96:99], v0 offset:256
	ds_read_b128 v[100:103], v0 offset:384
	v_mov_b32_e32 v113, 0
	s_waitcnt lgkmcnt(3)
	v_lshlrev_b32_e32 v104, 16, v88
	v_and_b32_e32 v105, 0xffff0000, v88
	v_lshlrev_b32_e32 v88, 16, v89
	v_and_b32_e32 v89, 0xffff0000, v89
	v_pk_fma_f32 v[104:105], v[36:37], v[104:105], v[40:41]
	s_waitcnt lgkmcnt(2)
	v_lshlrev_b32_e32 v106, 16, v92
	v_and_b32_e32 v107, 0xffff0000, v92
	v_pk_fma_f32 v[88:89], v[38:39], v[88:89], v[42:43]
	v_lshlrev_b32_e32 v92, 16, v93
	v_and_b32_e32 v93, 0xffff0000, v93
	v_pk_fma_f32 v[104:105], v[8:9], v[106:107], v[104:105]
	s_waitcnt lgkmcnt(1)
	v_lshlrev_b32_e32 v106, 16, v96
	v_and_b32_e32 v107, 0xffff0000, v96
	v_pk_fma_f32 v[88:89], v[10:11], v[92:93], v[88:89]
	v_lshlrev_b32_e32 v92, 16, v97
	v_and_b32_e32 v93, 0xffff0000, v97
	v_pk_fma_f32 v[104:105], v[12:13], v[106:107], v[104:105]
	s_waitcnt lgkmcnt(0)
	v_lshlrev_b32_e32 v106, 16, v100
	v_and_b32_e32 v107, 0xffff0000, v100
	v_pk_fma_f32 v[88:89], v[14:15], v[92:93], v[88:89]
	v_lshlrev_b32_e32 v92, 16, v101
	v_and_b32_e32 v93, 0xffff0000, v101
	v_pk_fma_f32 v[104:105], v[20:21], v[106:107], v[104:105]
	v_pk_fma_f32 v[106:107], v[22:23], v[92:93], v[88:89]
	v_lshlrev_b32_e32 v88, 16, v90
	v_and_b32_e32 v89, 0xffff0000, v90
	v_pk_fma_f32 v[88:89], v[28:29], v[88:89], v[32:33]
	v_lshlrev_b32_e32 v92, 16, v94
	v_and_b32_e32 v93, 0xffff0000, v94
	v_pk_fma_f32 v[88:89], v[4:5], v[92:93], v[88:89]
	v_lshlrev_b32_e32 v92, 16, v98
	v_and_b32_e32 v93, 0xffff0000, v98
	v_pk_fma_f32 v[88:89], v[16:17], v[92:93], v[88:89]
	v_lshlrev_b32_e32 v92, 16, v102
	v_and_b32_e32 v93, 0xffff0000, v102
	v_lshlrev_b32_e32 v90, 16, v91
	v_and_b32_e32 v91, 0xffff0000, v91
	v_pk_fma_f32 v[88:89], v[24:25], v[92:93], v[88:89]
	v_pk_fma_f32 v[90:91], v[30:31], v[90:91], v[34:35]
	v_lshlrev_b32_e32 v92, 16, v95
	v_and_b32_e32 v93, 0xffff0000, v95
	v_pk_fma_f32 v[90:91], v[6:7], v[92:93], v[90:91]
	v_lshlrev_b32_e32 v92, 16, v99
	v_and_b32_e32 v93, 0xffff0000, v99
	v_pk_fma_f32 v[90:91], v[18:19], v[92:93], v[90:91]
	v_lshlrev_b32_e32 v92, 16, v103
	v_and_b32_e32 v93, 0xffff0000, v103
	v_pk_fma_f32 v[90:91], v[26:27], v[92:93], v[90:91]
	ds_write_b128 v165, v[104:107] offset:2432
	ds_write_b128 v165, v[88:91] offset:2448
	ds_read_b128 v[88:91], v166
	ds_read_b128 v[92:95], v0 offset:1152
	ds_read_b128 v[96:99], v0 offset:1280
	ds_read_b128 v[100:103], v0 offset:1408
	v_add_u32_e32 v0, s19, v159
	s_waitcnt lgkmcnt(3)
	v_lshlrev_b32_e32 v104, 16, v88
	v_and_b32_e32 v105, 0xffff0000, v88
	v_lshlrev_b32_e32 v88, 16, v89
	v_and_b32_e32 v89, 0xffff0000, v89
	v_pk_fma_f32 v[104:105], v[36:37], v[104:105], v[40:41]
	s_waitcnt lgkmcnt(2)
	v_lshlrev_b32_e32 v106, 16, v92
	v_and_b32_e32 v107, 0xffff0000, v92
	v_pk_fma_f32 v[88:89], v[38:39], v[88:89], v[42:43]
	v_lshlrev_b32_e32 v92, 16, v93
	v_and_b32_e32 v93, 0xffff0000, v93
	v_pk_fma_f32 v[104:105], v[8:9], v[106:107], v[104:105]
	s_waitcnt lgkmcnt(1)
	v_lshlrev_b32_e32 v106, 16, v96
	v_and_b32_e32 v107, 0xffff0000, v96
	v_pk_fma_f32 v[88:89], v[10:11], v[92:93], v[88:89]
	v_lshlrev_b32_e32 v92, 16, v97
	v_and_b32_e32 v93, 0xffff0000, v97
	v_pk_fma_f32 v[104:105], v[12:13], v[106:107], v[104:105]
	s_waitcnt lgkmcnt(0)
	v_lshlrev_b32_e32 v106, 16, v100
	v_and_b32_e32 v107, 0xffff0000, v100
	v_pk_fma_f32 v[88:89], v[14:15], v[92:93], v[88:89]
	v_lshlrev_b32_e32 v92, 16, v101
	v_and_b32_e32 v93, 0xffff0000, v101
	v_pk_fma_f32 v[104:105], v[20:21], v[106:107], v[104:105]
	v_pk_fma_f32 v[106:107], v[22:23], v[92:93], v[88:89]
	v_lshlrev_b32_e32 v88, 16, v90
	v_and_b32_e32 v89, 0xffff0000, v90
	v_pk_fma_f32 v[88:89], v[28:29], v[88:89], v[32:33]
	v_lshlrev_b32_e32 v92, 16, v94
	v_and_b32_e32 v93, 0xffff0000, v94
	v_pk_fma_f32 v[88:89], v[4:5], v[92:93], v[88:89]
	v_lshlrev_b32_e32 v92, 16, v98
	v_and_b32_e32 v93, 0xffff0000, v98
	v_pk_fma_f32 v[88:89], v[16:17], v[92:93], v[88:89]
	v_lshlrev_b32_e32 v92, 16, v102
	v_and_b32_e32 v93, 0xffff0000, v102
	v_lshlrev_b32_e32 v90, 16, v91
	v_and_b32_e32 v91, 0xffff0000, v91
	v_pk_fma_f32 v[88:89], v[24:25], v[92:93], v[88:89]
	v_pk_fma_f32 v[90:91], v[30:31], v[90:91], v[34:35]
	v_lshlrev_b32_e32 v92, 16, v95
	v_and_b32_e32 v93, 0xffff0000, v95
	v_pk_fma_f32 v[90:91], v[6:7], v[92:93], v[90:91]
	v_lshlrev_b32_e32 v92, 16, v99
	v_and_b32_e32 v93, 0xffff0000, v99
	v_pk_fma_f32 v[90:91], v[18:19], v[92:93], v[90:91]
	v_lshlrev_b32_e32 v92, 16, v103
	v_and_b32_e32 v93, 0xffff0000, v103
	v_pk_fma_f32 v[90:91], v[26:27], v[92:93], v[90:91]
	ds_write_b128 v165, v[104:107] offset:4608
	ds_write_b128 v165, v[88:91] offset:4624
	s_waitcnt lgkmcnt(0)
	ds_read_b128 v[88:91], v167 offset:2432
	ds_read_b128 v[92:95], v167 offset:2448
	s_waitcnt lgkmcnt(1)
	v_cvt_pk_bf16_f32 v88, v88, v89
	v_cvt_pk_bf16_f32 v89, v90, v91
	s_waitcnt lgkmcnt(0)
	v_cvt_pk_bf16_f32 v90, v92, v93
	v_cvt_pk_bf16_f32 v91, v94, v95
	ds_read_b128 v[92:95], v167 offset:2560
	ds_read_b128 v[96:99], v167 offset:2576
	s_waitcnt lgkmcnt(1)
	v_cvt_pk_bf16_f32 v92, v92, v93
	v_cvt_pk_bf16_f32 v93, v94, v95
	s_waitcnt lgkmcnt(0)
	v_cvt_pk_bf16_f32 v94, v96, v97
	v_cvt_pk_bf16_f32 v95, v98, v99
	ds_read_b128 v[96:99], v127
	ds_read_b128 v[100:103], v128
	ds_read_b128 v[104:107], v122 offset:8192
	s_waitcnt lgkmcnt(2)
	v_mfma_f32_16x16x32_bf16 v[96:99], v[44:47], v[88:91], v[96:99]
	v_cmp_gt_i32_e64 s[16:17], s86, v0
	v_mov_b32_e32 v112, 0
	s_waitcnt lgkmcnt(0)
	v_mfma_f32_16x16x32_bf16 v[100:103], v[104:107], v[88:91], v[100:103]
	v_mfma_f32_16x16x32_bf16 v[104:107], v[48:51], v[92:95], v[96:99]
	s_nop 2
	ds_read_b128 v[96:99], v122 offset:9216
	s_waitcnt lgkmcnt(0)
; #define LAS __attribute__((address_space(3)))
; #define MFMA16(a, b, c) __builtin_amdgcn_mfma_f32_16x16x32_bf16((a), (b), (c), 0, 0, 0)
; template <int DIR>
; __device__ __forceinline__ void rnn_scan_unit(const Params& p, LAS unsigned char* lds, int b, int g) {
;     ...
;           for (int n = 0; n < 4; ++n) { const int c4 = 16 * n + 4 * fq;
;               f32x4 ra = *(const LAS f32x4*)(cst + c4), ia = *(const LAS f32x4*)(cst + 64 + c4);
; #pragma unroll
;               for (int ks = 0; ks < 2; ++ks) { ra = MFMA16(wreg[(0 * 4 + n) * 2 + ks], af[ks], ra); ia = MFMA16(wl[((1 * 4 + n) * 2 + ks) * 64 + lane], af[ks], ia); }
;               const f32x4 xv = *(const LAS f32x4*)(xcf + tt * XS + c4);
;               const f32x4 spv = *(const LAS f32x4*)(cst + 128 + c4);
;               f32x4 av, bv;
; #pragma unroll
;               for (int i = 0; i < 4; ++i) { const float r = __builtin_amdgcn_rcpf(1.0f + __builtin_amdgcn_exp2f(ra[i])), ig = __builtin_amdgcn_rcpf(1.0f + __builtin_amdgcn_exp2f(ia[i]));
;                   const float a = __builtin_amdgcn_exp2f(r * spv[i]); const float em = fmaf(-a, a, 1.0f);
;                   av[i] = valid ? a : 1.0f; bv[i] = valid ? __builtin_amdgcn_sqrtf(fmaxf(em, 0.0f)) * ig * xv[i] : 0.0f; }
;               *(LAS f32x4*)(al + tt * 64 + c4) = av; *(LAS f32x4*)(bl + tt * 64 + c4) = bv; } }
	v_mfma_f32_16x16x32_bf16 v[100:103], v[96:99], v[92:95], v[100:103]
	s_nop 1
	ds_read_b128 v[96:99], v129 offset:2432
	ds_read_b128 v[108:111], v130
	v_exp_f32_e32 v104, v104
	v_exp_f32_e32 v105, v105
	v_exp_f32_e32 v106, v106
	v_exp_f32_e32 v107, v107
	v_exp_f32_e32 v100, v100
	v_exp_f32_e32 v101, v101
	v_exp_f32_e32 v102, v102
	v_exp_f32_e32 v103, v103
	v_add_f32_e32 v104, 1.0, v104
	v_add_f32_e32 v105, 1.0, v105
	v_add_f32_e32 v106, 1.0, v106
	v_add_f32_e32 v107, 1.0, v107
	v_add_f32_e32 v100, 1.0, v100
	v_add_f32_e32 v101, 1.0, v101
	v_add_f32_e32 v102, 1.0, v102
	v_add_f32_e32 v103, 1.0, v103
	v_rcp_f32_e32 v104, v104
	v_rcp_f32_e32 v105, v105
	v_rcp_f32_e32 v106, v106
	v_rcp_f32_e32 v107, v107
	v_rcp_f32_e32 v100, v100
	v_rcp_f32_e32 v101, v101
	v_rcp_f32_e32 v102, v102
	v_rcp_f32_e32 v103, v103
	s_waitcnt lgkmcnt(0)
	v_mul_f32_e32 v104, v104, v108
	v_mul_f32_e32 v105, v105, v109
	v_mul_f32_e32 v106, v106, v110
	v_mul_f32_e32 v107, v107, v111
	v_exp_f32_e32 v104, v104
	v_exp_f32_e32 v105, v105
	v_exp_f32_e32 v106, v106
	v_exp_f32_e32 v107, v107
	v_fma_f32 v112, -v104, v104, 1.0
	v_fma_f32 v113, -v105, v105, 1.0
	v_fma_f32 v114, -v106, v106, 1.0
	v_fma_f32 v115, -v107, v107, 1.0
	v_max_f32_e32 v112, 0, v112
	v_max_f32_e32 v113, 0, v113
	v_max_f32_e32 v114, 0, v114
	v_max_f32_e32 v115, 0, v115
	v_sqrt_f32_e32 v112, v112
	v_sqrt_f32_e32 v113, v113
	v_sqrt_f32_e32 v114, v114
	v_sqrt_f32_e32 v115, v115
	v_mul_f32_e32 v100, v100, v112
	v_mul_f32_e32 v101, v101, v113
	v_mul_f32_e32 v102, v102, v114
	v_mul_f32_e32 v103, v103, v115
	v_mul_f32_e32 v112, v96, v100
	v_mul_f32_e32 v113, v97, v101
	v_mul_f32_e32 v114, v98, v102
	v_mul_f32_e32 v115, v99, v103
	v_cndmask_b32_e64 v112, 0, v112, s[16:17]
	v_cndmask_b32_e64 v113, 0, v113, s[16:17]
	v_cndmask_b32_e64 v114, 0, v114, s[16:17]
	v_cndmask_b32_e64 v115, 0, v115, s[16:17]
	v_cndmask_b32_e64 v98, 1.0, v104, s[16:17]
	v_cndmask_b32_e64 v99, 1.0, v105, s[16:17]
	v_cndmask_b32_e64 v100, 1.0, v106, s[16:17]
	v_cndmask_b32_e64 v101, 1.0, v107, s[16:17]
	ds_write_b128 v131, v[98:101] offset:6784
	ds_write_b128 v131, v[112:115] offset:10880
	ds_read_b128 v[96:99], v132
	ds_read_b128 v[100:103], v133
	ds_read_b128 v[104:107], v122 offset:10240
	s_waitcnt lgkmcnt(2)
	v_mfma_f32_16x16x32_bf16 v[96:99], v[52:55], v[88:91], v[96:99]
	v_mov_b32_e32 v113, 0
	v_mov_b32_e32 v112, 0
	s_waitcnt lgkmcnt(0)
	v_mfma_f32_16x16x32_bf16 v[100:103], v[104:107], v[88:91], v[100:103]
	v_mfma_f32_16x16x32_bf16 v[104:107], v[56:59], v[92:95], v[96:99]
	s_nop 2
	ds_read_b128 v[96:99], v122 offset:11264
	s_waitcnt lgkmcnt(0)
	v_mfma_f32_16x16x32_bf16 v[96:99], v[96:99], v[92:95], v[100:103]
	s_nop 1
	ds_read_b128 v[100:103], v129 offset:2496
	ds_read_b128 v[108:111], v134
	v_exp_f32_e32 v104, v104
	v_exp_f32_e32 v105, v105
	v_exp_f32_e32 v106, v106
	v_exp_f32_e32 v107, v107
	v_exp_f32_e32 v96, v96
	v_exp_f32_e32 v97, v97
	v_exp_f32_e32 v98, v98
	v_exp_f32_e32 v99, v99
	v_add_f32_e32 v104, 1.0, v104
	v_add_f32_e32 v105, 1.0, v105
	v_add_f32_e32 v106, 1.0, v106
	v_add_f32_e32 v107, 1.0, v107
	v_add_f32_e32 v96, 1.0, v96
	v_add_f32_e32 v97, 1.0, v97
	v_add_f32_e32 v98, 1.0, v98
	v_add_f32_e32 v99, 1.0, v99
	v_rcp_f32_e32 v104, v104
	v_rcp_f32_e32 v105, v105
	v_rcp_f32_e32 v106, v106
	v_rcp_f32_e32 v107, v107
	v_rcp_f32_e32 v96, v96
	v_rcp_f32_e32 v97, v97
	v_rcp_f32_e32 v98, v98
	v_rcp_f32_e32 v99, v99
	s_waitcnt lgkmcnt(0)
	v_mul_f32_e32 v104, v104, v108
	v_mul_f32_e32 v105, v105, v109
	v_mul_f32_e32 v106, v106, v110
	v_mul_f32_e32 v107, v107, v111
	v_exp_f32_e32 v104, v104
	v_exp_f32_e32 v105, v105
	v_exp_f32_e32 v106, v106
	v_exp_f32_e32 v107, v107
	v_fma_f32 v112, -v104, v104, 1.0
	v_fma_f32 v113, -v105, v105, 1.0
	v_fma_f32 v114, -v106, v106, 1.0
	v_fma_f32 v115, -v107, v107, 1.0
	v_max_f32_e32 v112, 0, v112
	v_max_f32_e32 v113, 0, v113
	v_max_f32_e32 v114, 0, v114
	v_max_f32_e32 v115, 0, v115
	v_sqrt_f32_e32 v112, v112
	v_sqrt_f32_e32 v113, v113
	v_sqrt_f32_e32 v114, v114
	v_sqrt_f32_e32 v115, v115
	v_mul_f32_e32 v96, v96, v112
	v_mul_f32_e32 v97, v97, v113
	v_mul_f32_e32 v98, v98, v114
	v_mul_f32_e32 v99, v99, v115
	v_mul_f32_e32 v112, v100, v96
	v_mul_f32_e32 v113, v101, v97
	v_mul_f32_e32 v114, v102, v98
	v_mul_f32_e32 v115, v103, v99
	v_cndmask_b32_e64 v112, 0, v112, s[16:17]
	v_cndmask_b32_e64 v113, 0, v113, s[16:17]
	v_cndmask_b32_e64 v114, 0, v114, s[16:17]
	v_cndmask_b32_e64 v115, 0, v115, s[16:17]
	v_cndmask_b32_e64 v98, 1.0, v104, s[16:17]
	v_cndmask_b32_e64 v99, 1.0, v105, s[16:17]
	v_cndmask_b32_e64 v100, 1.0, v106, s[16:17]
	v_cndmask_b32_e64 v101, 1.0, v107, s[16:17]
	ds_write_b128 v131, v[98:101] offset:6848
	ds_write_b128 v131, v[112:115] offset:10944
	ds_read_b128 v[96:99], v135
	ds_read_b128 v[100:103], v136
	ds_read_b128 v[104:107], v122 offset:12288
	s_waitcnt lgkmcnt(2)
	v_mfma_f32_16x16x32_bf16 v[96:99], v[60:63], v[88:91], v[96:99]
	v_mov_b32_e32 v113, 0
	v_mov_b32_e32 v112, 0
	s_waitcnt lgkmcnt(0)
	v_mfma_f32_16x16x32_bf16 v[100:103], v[104:107], v[88:91], v[100:103]
	v_mfma_f32_16x16x32_bf16 v[104:107], v[64:67], v[92:95], v[96:99]
	s_nop 2
	ds_read_b128 v[96:99], v122 offset:13312
	s_waitcnt lgkmcnt(0)
	v_mfma_f32_16x16x32_bf16 v[96:99], v[96:99], v[92:95], v[100:103]
	s_nop 1
	ds_read_b128 v[100:103], v129 offset:2560
	ds_read_b128 v[108:111], v137
	v_exp_f32_e32 v104, v104
	v_exp_f32_e32 v105, v105
	v_exp_f32_e32 v106, v106
	v_exp_f32_e32 v107, v107
	v_exp_f32_e32 v96, v96
	v_exp_f32_e32 v97, v97
	v_exp_f32_e32 v98, v98
	v_exp_f32_e32 v99, v99
	v_add_f32_e32 v104, 1.0, v104
	v_add_f32_e32 v105, 1.0, v105
	v_add_f32_e32 v106, 1.0, v106
	v_add_f32_e32 v107, 1.0, v107
	v_add_f32_e32 v96, 1.0, v96
	v_add_f32_e32 v97, 1.0, v97
	v_add_f32_e32 v98, 1.0, v98
	v_add_f32_e32 v99, 1.0, v99
	v_rcp_f32_e32 v104, v104
	v_rcp_f32_e32 v105, v105
	v_rcp_f32_e32 v106, v106
	v_rcp_f32_e32 v107, v107
	v_rcp_f32_e32 v96, v96
	v_rcp_f32_e32 v97, v97
	v_rcp_f32_e32 v98, v98
	v_rcp_f32_e32 v99, v99
	s_waitcnt lgkmcnt(0)
; #define LAS __attribute__((address_space(3)))
; #define MFMA16(a, b, c) __builtin_amdgcn_mfma_f32_16x16x32_bf16((a), (b), (c), 0, 0, 0)
; #define LDS_BARRIER() asm volatile("s_waitcnt lgkmcnt(0)\n\ts_barrier" ::: "memory")
; template <int DIR>
; __device__ __forceinline__ void rnn_scan_unit(const Params& p, LAS unsigned char* lds, int b, int g) {
;     ...
;           for (int n = 0; n < 4; ++n) { const int c4 = 16 * n + 4 * fq;
;               f32x4 ra = *(const LAS f32x4*)(cst + c4), ia = *(const LAS f32x4*)(cst + 64 + c4);
; #pragma unroll
;               for (int ks = 0; ks < 2; ++ks) { ra = MFMA16(wreg[(0 * 4 + n) * 2 + ks], af[ks], ra); ia = MFMA16(wl[((1 * 4 + n) * 2 + ks) * 64 + lane], af[ks], ia); }
;               const f32x4 xv = *(const LAS f32x4*)(xcf + tt * XS + c4);
;               const f32x4 spv = *(const LAS f32x4*)(cst + 128 + c4);
;               f32x4 av, bv;
; #pragma unroll
;               for (int i = 0; i < 4; ++i) { const float r = __builtin_amdgcn_rcpf(1.0f + __builtin_amdgcn_exp2f(ra[i])), ig = __builtin_amdgcn_rcpf(1.0f + __builtin_amdgcn_exp2f(ia[i]));
;                   const float a = __builtin_amdgcn_exp2f(r * spv[i]); const float em = fmaf(-a, a, 1.0f);
;                   av[i] = valid ? a : 1.0f; bv[i] = valid ? __builtin_amdgcn_sqrtf(fmaxf(em, 0.0f)) * ig * xv[i] : 0.0f; }
;               *(LAS f32x4*)(al + tt * 64 + c4) = av; *(LAS f32x4*)(bl + tt * 64 + c4) = bv; } }
;         asm volatile("s_waitcnt lgkmcnt(0)" ::: "memory");
;         LAS float* sgA = sg + (ci & 1) * 1024; LAS float* sgB = sgA + 512;
;         float av_[16], bv_[16];
;         { float A = 1.f, B = 0.f;
; #pragma unroll
;           for (int k = 0; k < 16; ++k) { const int tt = DIR == 0 ? k : 15 - k; av_[k] = al[tt * 64 + ch]; bv_[k] = bl[tt * 64 + ch]; B = av_[k] * B + bv_[k]; A *= av_[k]; }
;           sgA[seg * 64 + ch] = A; sgB[seg * 64 + ch] = B; }
;         LDS_BARRIER();
	v_mul_f32_e32 v104, v104, v108
	v_mul_f32_e32 v105, v105, v109
	v_mul_f32_e32 v106, v106, v110
	v_mul_f32_e32 v107, v107, v111
	v_exp_f32_e32 v104, v104
	v_exp_f32_e32 v105, v105
	v_exp_f32_e32 v106, v106
	v_exp_f32_e32 v107, v107
	v_fma_f32 v112, -v104, v104, 1.0
	v_fma_f32 v113, -v105, v105, 1.0
	v_fma_f32 v114, -v106, v106, 1.0
	v_fma_f32 v115, -v107, v107, 1.0
	v_max_f32_e32 v112, 0, v112
	v_max_f32_e32 v113, 0, v113
	v_max_f32_e32 v114, 0, v114
	v_max_f32_e32 v115, 0, v115
	v_sqrt_f32_e32 v112, v112
	v_sqrt_f32_e32 v113, v113
	v_sqrt_f32_e32 v114, v114
	v_sqrt_f32_e32 v115, v115
	v_mul_f32_e32 v96, v96, v112
	v_mul_f32_e32 v97, v97, v113
	v_mul_f32_e32 v98, v98, v114
	v_mul_f32_e32 v99, v99, v115
	v_mul_f32_e32 v112, v100, v96
	v_mul_f32_e32 v113, v101, v97
	v_mul_f32_e32 v114, v102, v98
	v_mul_f32_e32 v115, v103, v99
	v_cndmask_b32_e64 v112, 0, v112, s[16:17]
	v_cndmask_b32_e64 v113, 0, v113, s[16:17]
	v_cndmask_b32_e64 v114, 0, v114, s[16:17]
	v_cndmask_b32_e64 v115, 0, v115, s[16:17]
	v_cndmask_b32_e64 v98, 1.0, v104, s[16:17]
	v_cndmask_b32_e64 v99, 1.0, v105, s[16:17]
	v_cndmask_b32_e64 v100, 1.0, v106, s[16:17]
	v_cndmask_b32_e64 v101, 1.0, v107, s[16:17]
	ds_write_b128 v131, v[98:101] offset:6912
	ds_write_b128 v131, v[112:115] offset:11008
	ds_read_b128 v[96:99], v138
	ds_read_b128 v[100:103], v139
	ds_read_b128 v[104:107], v122 offset:14336
	s_waitcnt lgkmcnt(2)
	v_mfma_f32_16x16x32_bf16 v[96:99], v[68:71], v[88:91], v[96:99]
	s_waitcnt lgkmcnt(0)
	v_mfma_f32_16x16x32_bf16 v[88:91], v[104:107], v[88:91], v[100:103]
	v_mov_b32_e32 v105, 0
	s_nop 1
	ds_read_b128 v[100:103], v122 offset:15360
	v_mov_b32_e32 v104, 0
	v_mfma_f32_16x16x32_bf16 v[96:99], v[72:75], v[92:95], v[96:99]
	s_waitcnt lgkmcnt(0)
	v_mfma_f32_16x16x32_bf16 v[88:91], v[100:103], v[92:95], v[88:91]
	ds_read_b128 v[92:95], v129 offset:2624
	ds_read_b128 v[100:103], v154
	s_nop 3
	v_exp_f32_e32 v96, v96
	v_exp_f32_e32 v97, v97
	v_exp_f32_e32 v98, v98
	v_exp_f32_e32 v99, v99
	v_exp_f32_e32 v88, v88
	v_exp_f32_e32 v89, v89
	v_exp_f32_e32 v90, v90
	v_exp_f32_e32 v91, v91
	v_add_f32_e32 v96, 1.0, v96
	v_add_f32_e32 v97, 1.0, v97
	v_add_f32_e32 v98, 1.0, v98
	v_add_f32_e32 v99, 1.0, v99
	v_add_f32_e32 v88, 1.0, v88
	v_add_f32_e32 v89, 1.0, v89
	v_add_f32_e32 v90, 1.0, v90
	v_add_f32_e32 v91, 1.0, v91
	v_rcp_f32_e32 v96, v96
	v_rcp_f32_e32 v97, v97
	v_rcp_f32_e32 v98, v98
	v_rcp_f32_e32 v99, v99
	v_rcp_f32_e32 v88, v88
	v_rcp_f32_e32 v89, v89
	v_rcp_f32_e32 v90, v90
	v_rcp_f32_e32 v91, v91
	s_waitcnt lgkmcnt(0)
	v_mul_f32_e32 v96, v96, v100
	v_mul_f32_e32 v97, v97, v101
	v_mul_f32_e32 v98, v98, v102
	v_mul_f32_e32 v99, v99, v103
	v_exp_f32_e32 v96, v96
	v_exp_f32_e32 v97, v97
	v_exp_f32_e32 v98, v98
	v_exp_f32_e32 v99, v99
	v_fma_f32 v104, -v96, v96, 1.0
	v_fma_f32 v105, -v97, v97, 1.0
	v_fma_f32 v106, -v98, v98, 1.0
	v_fma_f32 v107, -v99, v99, 1.0
	v_max_f32_e32 v104, 0, v104
	v_max_f32_e32 v105, 0, v105
	v_max_f32_e32 v106, 0, v106
	v_max_f32_e32 v107, 0, v107
	v_sqrt_f32_e32 v104, v104
	v_sqrt_f32_e32 v105, v105
	v_sqrt_f32_e32 v106, v106
	v_sqrt_f32_e32 v107, v107
	v_mul_f32_e32 v88, v88, v104
	v_mul_f32_e32 v89, v89, v105
	v_mul_f32_e32 v90, v90, v106
	v_mul_f32_e32 v91, v91, v107
	v_mul_f32_e32 v104, v92, v88
	v_mul_f32_e32 v105, v93, v89
	v_mul_f32_e32 v106, v94, v90
	v_mul_f32_e32 v107, v95, v91
	v_cndmask_b32_e64 v104, 0, v104, s[16:17]
	v_cndmask_b32_e64 v105, 0, v105, s[16:17]
	v_cndmask_b32_e64 v106, 0, v106, s[16:17]
	v_cndmask_b32_e64 v107, 0, v107, s[16:17]
	v_cndmask_b32_e64 v90, 1.0, v96, s[16:17]
	v_cndmask_b32_e64 v91, 1.0, v97, s[16:17]
	v_cndmask_b32_e64 v92, 1.0, v98, s[16:17]
	v_cndmask_b32_e64 v93, 1.0, v99, s[16:17]
	ds_write_b128 v131, v[90:93] offset:6976
	ds_write_b128 v131, v[104:107] offset:11072
	s_waitcnt lgkmcnt(0)
	v_add_u32_e32 v176, 0x80, v124
	ds_read2st64_b32 v[88:89], v176 offset0:26 offset1:27
	ds_read2st64_b32 v[90:91], v176 offset0:42 offset1:43
	ds_read2st64_b32 v[94:95], v176 offset0:28 offset1:29
	ds_read2st64_b32 v[92:93], v176 offset0:44 offset1:45
	ds_read2st64_b32 v[98:99], v176 offset0:30 offset1:31
	ds_read2st64_b32 v[96:97], v176 offset0:46 offset1:47
	ds_read2st64_b32 v[100:101], v176 offset0:32 offset1:33
	ds_read2st64_b32 v[102:103], v176 offset0:48 offset1:49
	s_waitcnt lgkmcnt(7)
	v_mul_f32_e32 v2, v88, v89
	s_waitcnt lgkmcnt(6)
	v_fma_f32 v0, 0, v88, v90
	v_fma_f32 v0, v0, v89, v91
	s_waitcnt lgkmcnt(4)
	v_fma_f32 v0, v0, v94, v92
	v_mul_f32_e32 v2, v2, v94
	v_fma_f32 v0, v0, v95, v93
	v_mul_f32_e32 v2, v2, v95
	ds_read2st64_b32 v[104:105], v176 offset0:34 offset1:35
	ds_read2st64_b32 v[106:107], v176 offset0:50 offset1:51
	s_waitcnt lgkmcnt(4)
	v_fma_f32 v0, v0, v98, v96
	v_mul_f32_e32 v2, v2, v98
	v_fma_f32 v0, v0, v99, v97
	v_mul_f32_e32 v2, v2, v99
	ds_read2st64_b32 v[110:111], v176 offset0:36 offset1:37
	ds_read2st64_b32 v[108:109], v176 offset0:52 offset1:53
	s_waitcnt lgkmcnt(4)
	v_fma_f32 v0, v0, v100, v102
	v_mul_f32_e32 v2, v2, v100
	v_fma_f32 v0, v0, v101, v103
	v_mul_f32_e32 v2, v2, v101
	ds_read2st64_b32 v[114:115], v176 offset0:38 offset1:39
	ds_read2st64_b32 v[168:169], v176 offset0:54 offset1:55
	s_waitcnt lgkmcnt(4)
	v_fma_f32 v0, v0, v104, v106
	v_mul_f32_e32 v2, v2, v104
	v_fma_f32 v0, v0, v105, v107
	v_mul_f32_e32 v2, v2, v105
	ds_read2st64_b32 v[170:171], v176 offset0:40 offset1:41
	ds_read2st64_b32 v[172:173], v176 offset0:56 offset1:57
	s_waitcnt lgkmcnt(4)
	v_fma_f32 v0, v0, v110, v108
	v_mul_f32_e32 v2, v2, v110
	s_and_b32 s16, s34, 0x400
	v_fma_f32 v0, v0, v111, v109
	v_mul_f32_e32 v2, v2, v111
	s_lshl_b32 s16, s16, 2
	s_waitcnt lgkmcnt(2)
	v_fma_f32 v0, v0, v114, v168
	v_mul_f32_e32 v2, v2, v114
	s_add_i32 s16, s16, 0
	v_fma_f32 v0, v0, v115, v169
	v_mul_f32_e32 v2, v2, v115
	s_add_i32 s16, s16, 0x1d400
	s_waitcnt lgkmcnt(0)
	v_fma_f32 v0, v0, v170, v172
	v_mul_f32_e32 v2, v2, v170
	v_fma_f32 v0, v0, v171, v173
	v_mul_f32_e32 v2, v2, v171
	v_lshl_add_u32 v112, v120, 2, s16
	ds_write2st64_b32 v112, v2, v0 offset1:8
	s_waitcnt lgkmcnt(0)
	s_barrier
; #define LAS __attribute__((address_space(3)))
; __device__ __forceinline__ unsigned cvt_pk(float lo, float hi) { unsigned r; asm("v_cvt_pk_bf16_f32 %0, %1, %2" : "=v"(r) : "v"(lo), "v"(hi)); return r; }
; template <int DIR>
; __device__ __forceinline__ void rnn_scan_unit(const Params& p, LAS unsigned char* lds, int b, int g) {
;     ...
;         float h = hcar, hin = hcar;
; #pragma unroll
;         for (int s = 0; s < 8; ++s) { const int sx = DIR == 0 ? s : 7 - s; hin = (sx == seg) ? h : hin; h = sgA[sx * 64 + ch] * h + sgB[sx * 64 + ch]; }
;         hcar = h;
; #pragma unroll
;         for (int k = 0; k < 16; ++k) { const int tt = DIR == 0 ? k : 15 - k; hin = av_[k] * hin + bv_[k]; bl[tt * 64 + ch] = hin; }
;         asm volatile("s_waitcnt lgkmcnt(0)" ::: "memory");
;         { const int tk = lane >> 2, cq4 = lane & 3;
;           if (t0 + tk < TT) { const LAS float* src = bl + tk * 64 + 16 * cq4;
;               const f32x4 x0 = *(const LAS f32x4*)(src), x1 = *(const LAS f32x4*)(src + 4), x2 = *(const LAS f32x4*)(src + 8), x3 = *(const LAS f32x4*)(src + 12);
;               u32x4 w0, w1; w0.x = cvt_pk(x0[0], x0[1]); w0.y = cvt_pk(x0[2], x0[3]); w0.z = cvt_pk(x1[0], x1[1]); w0.w = cvt_pk(x1[2], x1[3]);
;               w1.x = cvt_pk(x2[0], x2[1]); w1.y = cvt_pk(x2[2], x2[3]); w1.z = cvt_pk(x3[0], x3[1]); w1.w = cvt_pk(x3[2], x3[3]);
;               bf16_t* hp = H + ((size_t)b * TT + t0 + tk) * 512 + 64 * g + 16 * cq4;
;               *(u32x4*)hp = w0; *(u32x4*)(hp + 8) = w1; } }
;         asm volatile("s_waitcnt lgkmcnt(0)" ::: "memory");
	v_lshl_add_u32 v0, v121, 2, s16
	ds_read2st64_b32 v[112:113], v0 offset1:1
	ds_read2st64_b32 v[174:175], v0 offset0:8 offset1:9
	s_waitcnt lgkmcnt(0)
	v_fma_f32 v2, v3, v112, v174
	v_cndmask_b32_e64 v3, v3, v2, s[0:1]
	v_fmac_f32_e32 v175, v2, v113
	v_cndmask_b32_e64 v174, v3, v175, s[2:3]
	ds_read2st64_b32 v[2:3], v0 offset0:2 offset1:3
	ds_read2st64_b32 v[112:113], v0 offset0:10 offset1:11
	s_waitcnt lgkmcnt(0)
	v_fma_f32 v2, v175, v2, v112
	v_cndmask_b32_e64 v112, v174, v2, s[4:5]
	v_fmac_f32_e32 v113, v2, v3
	ds_read2st64_b32 v[2:3], v0 offset0:4 offset1:5
	ds_read2st64_b32 v[174:175], v0 offset0:12 offset1:13
	v_cndmask_b32_e64 v112, v112, v113, s[8:9]
	s_waitcnt lgkmcnt(0)
	v_fma_f32 v2, v113, v2, v174
	v_cndmask_b32_e64 v112, v112, v2, s[10:11]
	v_fmac_f32_e32 v175, v2, v3
	v_cndmask_b32_e64 v174, v112, v175, s[12:13]
	ds_read2st64_b32 v[112:113], v0 offset0:6 offset1:7
	ds_read2st64_b32 v[2:3], v0 offset0:14 offset1:15
	s_waitcnt lgkmcnt(0)
	v_fma_f32 v0, v175, v112, v2
	v_cndmask_b32_e64 v2, v174, v0, s[14:15]
	v_fma_f32 v2, v88, v2, v90
	v_fmac_f32_e32 v91, v89, v2
	ds_write2st64_b32 v176, v2, v91 offset0:42 offset1:43
	v_fma_f32 v2, v94, v91, v92
	v_fmac_f32_e32 v93, v95, v2
	ds_write2st64_b32 v176, v2, v93 offset0:44 offset1:45
	v_fma_f32 v2, v98, v93, v96
	v_fmac_f32_e32 v97, v99, v2
	ds_write2st64_b32 v176, v2, v97 offset0:46 offset1:47
	v_fma_f32 v2, v100, v97, v102
	v_fmac_f32_e32 v103, v101, v2
	ds_write2st64_b32 v176, v2, v103 offset0:48 offset1:49
	v_fma_f32 v2, v104, v103, v106
	v_fmac_f32_e32 v107, v105, v2
	ds_write2st64_b32 v176, v2, v107 offset0:50 offset1:51
	v_fma_f32 v2, v110, v107, v108
	v_fmac_f32_e32 v109, v111, v2
	ds_write2st64_b32 v176, v2, v109 offset0:52 offset1:53
	v_fma_f32 v2, v114, v109, v168
	v_fmac_f32_e32 v169, v115, v2
	ds_write2st64_b32 v176, v2, v169 offset0:54 offset1:55
	v_fma_f32 v2, v170, v169, v172
	v_fmac_f32_e32 v173, v171, v2
	ds_write2st64_b32 v176, v2, v173 offset0:56 offset1:57
	s_waitcnt lgkmcnt(0)
	v_add_u32_e32 v2, s19, v158
	v_cmp_gt_i32_e64 s[16:17], s86, v2
	s_and_saveexec_b64 s[76:77], s[16:17]
	s_cbranch_execz .LBB0_595
	ds_read_b128 v[88:91], v125 offset:10880
	ds_read_b128 v[92:95], v125 offset:10896
	ds_read_b128 v[96:99], v125 offset:10912
	ds_read_b128 v[100:103], v125 offset:10928
	s_waitcnt lgkmcnt(3)
	v_cvt_pk_bf16_f32 v88, v88, v89
	v_cvt_pk_bf16_f32 v89, v90, v91
	s_waitcnt lgkmcnt(2)
	v_cvt_pk_bf16_f32 v90, v92, v93
	v_cvt_pk_bf16_f32 v91, v94, v95
	s_waitcnt lgkmcnt(1)
	v_cvt_pk_bf16_f32 v92, v96, v97
	v_cvt_pk_bf16_f32 v93, v98, v99
	s_waitcnt lgkmcnt(0)
	v_cvt_pk_bf16_f32 v94, v100, v101
	v_cvt_pk_bf16_f32 v95, v102, v103
	global_store_dwordx4 v[118:119], v[88:91], off
	global_store_dwordx4 v[118:119], v[92:95], off offset:16
	s_branch .LBB0_595
